# static priority: waves 4-7 at s_setprio 1 for the whole FoX phase (reset after every phase)
# baseline (speedup 1.0000x reference)
; #define SBAR() __builtin_amdgcn_sched_barrier(0)
; #define VMW() asm volatile("s_waitcnt vmcnt(0)" ::: "memory")
; #define SLOAD_H(Kp, Vp, k0) do { S.st_v0 = load8<TIn>(ROW(Vp, k0, sr)); S.st_v1 = load8<TIn>(ROW(Vp, k0, 32 + sr));              \
;                          S.st_k0 = load8<TIn>(ROW(Kp, k0, sr)); S.st_k1 = load8<TIn>(ROW(Kp, k0, 32 + sr)); } while (0)
; #define SWRITE_HK(bf) do { *(bf16x8*)(K_lds + (bf) * SHM_K + kws) = S.st_k0; *(bf16x8*)(K_lds + (bf) * SHM_K + kws + 32 * 256) = S.st_k1; } while (0)
; #define SLOAD_F(p, k0) do { S.sf0 = *(const f32x4*)ROW(p, k0, sr); S.sf1 = *(const f32x4*)(ROW(p, k0, sr) + 4);                \
;                             S.sf2 = *(const f32x4*)ROW(p, k0, 32 + sr); S.sf3 = *(const f32x4*)(ROW(p, k0, 32 + sr) + 4); } while (0)
; template <class TIn, class TOut>
; __device__ __forceinline__ void causal_swa_prime(const BlockRef<TIn, TOut>& cur, int W, char* lds, Seam<TIn>& S, const int tid) {
;     constexpr bool F32 = same_t<TIn, float>::v;
;     const int wid = __builtin_amdgcn_readfirstlane(tid >> 6), lane = tid & 63, r32 = lane & 31, hi = lane >> 5;
;     const int sr = tid >> 4, sc = (tid & 15) * 8, kws = KSWZ(sr, sc * 2); char* K_lds = lds + 2 * SHM_V;
;     const int kb0 = swa_jlo(cur.P0, W) * KVBLK;
;     for (int d0 = 0; d0 < 8; ++d0) S.qr[d0] = load8<TIn>(cur.Q + (unsigned)((wid * QBLK + r32) * D + d0 * 16 + hi * 8));
;     if constexpr (F32) { SLOAD_F((const float*)cur.K, kb0); VMW(); SWRITE_KF(0); SBAR(); SLOAD_F((const float*)cur.V, kb0); }
;     else { SLOAD_H(cur.K, cur.V, kb0); BLOAD(S.pb0, S.pb1, cur.F, kb0); VMW(); SWRITE_HK(0); }
;     __syncthreads();
; }
; __device__ __forceinline__ void fox_phase(char* lds, const bf16* Q, const bf16* K, const bf16* V, const float* F, bf16* O, const int tid) {
;     constexpr int nb = 4, nh = 16, sq = 4096, skv = 4096, W = 4096, order = ORDER_PAIRED;
;     const int nqb = sq / QB, nramp = swa_nramp(nqb, W, 0), nx = swa_nx(nqb, nramp, order), total = nx * nb * nh, stride = gridDim.x;
;     int L = blockIdx.x; if (L >= total) return;
;     SwaItem it = swa_decode(L, nb, nh, nh, nqb, nx, nramp, order); int pass = 0;
;     BlockRef<bf16, bf16> cur = swa_ref<bf16, bf16>(it, 0, Q, K, V, F, O, nh, nh, sq, skv, 0);
;     Seam<bf16> S;
;     causal_swa_prime<bf16, bf16>(cur, W, lds, S, tid);
.LBB0_646:
	s_andn2_b64 vcc, exec, s[2:3]
	s_cbranch_vccnz .LBB0_826
	s_cmp_eq_u32 s46, 19
	s_cbranch_scc0 .LBB0_826
	v_readlane_b32 s0, v253, 5
	v_readlane_b32 s1, v253, 6
	s_andn2_b64 vcc, exec, s[0:1]
	s_cbranch_vccnz .LBB0_826
	v_readfirstlane_b32 s0, v194
	s_cmpk_lt_u32 s0, 0x100
	s_cbranch_scc1 .Lfox_noprio
	s_setprio 1
.Lfox_noprio:
	s_add_u32 s0, s30, 0x19e00000
	s_addc_u32 s1, s31, 0
	s_add_u32 s5, s30, 0x1de00000
	s_addc_u32 s35, s31, 0
	s_add_u32 s52, s30, 0x200000
	s_addc_u32 s53, s31, 0
	s_add_u32 s56, s30, 0x21e00000
	s_addc_u32 s57, s31, 0
	v_readlane_b32 s2, v253, 8
	v_readlane_b32 s3, v253, 9
	s_add_u32 s2, s36, s2
	s_addc_u32 s3, s37, s3
	v_readlane_b32 s6, v253, 10
	v_readlane_b32 s7, v253, 11
	s_add_u32 s12, s2, s6
	s_addc_u32 s13, s3, s7
	v_readlane_b32 s2, v253, 12
	v_readlane_b32 s3, v253, 13
	s_add_u32 s2, s56, s2
	s_addc_u32 s3, s57, s3
	v_readlane_b32 s6, v253, 14
	v_readlane_b32 s7, v253, 15
	s_add_u32 s2, s2, s6
	s_addc_u32 s3, s3, s7
	v_readlane_b32 s6, v253, 60
	v_readlane_b32 s7, v253, 61
	s_add_u32 s26, s2, s6
	s_addc_u32 s27, s3, s7
	v_readlane_b32 s2, v253, 62
	v_readlane_b32 s3, v253, 63
	s_add_u32 s42, s0, s2
	s_addc_u32 s43, s1, s3
	s_add_u32 s44, s5, s2
	s_addc_u32 s45, s35, s3
	v_readlane_b32 s2, v253, 18
	s_mov_b32 s71, s46
	v_readlane_b32 s3, v253, 19
	s_add_u32 s46, s52, s2
	v_readfirstlane_b32 s2, v194
	s_addc_u32 s47, s53, s3
	s_lshr_b32 s2, s2, 1
	s_and_b32 s8, s2, 0x1ffffe0
	v_readlane_b32 s6, v254, 0
	v_lshlrev_b32_e32 v8, 3, v194
	v_readlane_b32 s7, v254, 1
	s_add_u32 s2, s44, s6
	v_ashrrev_i32_e32 v1, 4, v194
	v_and_b32_e32 v9, 0x78, v8
	s_addc_u32 s3, s45, s7
	v_lshl_or_b32 v2, v1, 7, v9
	v_mov_b32_e32 v3, v0
	s_add_u32 s6, s42, s6
	v_lshlrev_b64 v[198:199], 1, v[2:3]
	v_add_u32_e32 v2, 0x1000, v2
	s_addc_u32 s7, s43, s7
	v_lshlrev_b64 v[2:3], 1, v[2:3]
	v_lshl_add_u64 v[4:5], s[6:7], 0, v[198:199]
	v_lshl_add_u64 v[6:7], s[6:7], 0, v[2:3]
	global_load_dwordx4 v[162:165], v[4:5], off
	global_load_dwordx4 v[166:169], v[6:7], off
	v_and_b32_e32 v195, 31, v194
	v_bfe_u32 v4, v194, 5, 1
	v_lshlrev_b32_e32 v6, 3, v4
	v_lshlrev_b32_e32 v12, 4, v4
	v_or_b32_e32 v4, s8, v195
	v_mov_b32_e32 v5, v0
	v_lshl_or_b32 v4, v4, 7, v6
	v_lshl_add_u64 v[4:5], v[4:5], 1, s[12:13]
	v_lshl_add_u64 v[6:7], s[2:3], 0, v[198:199]
	v_lshl_add_u64 v[2:3], s[2:3], 0, v[2:3]
	v_readlane_b32 s2, v254, 11
	global_load_dwordx4 v[158:161], v[4:5], off
	global_load_dwordx4 v[154:157], v[4:5], off offset:32
	global_load_dwordx4 v[150:153], v[4:5], off offset:64
	global_load_dwordx4 v[146:149], v[4:5], off offset:96
	global_load_dwordx4 v[142:145], v[4:5], off offset:128
	global_load_dwordx4 v[138:141], v[4:5], off offset:160
	global_load_dwordx4 v[134:137], v[4:5], off offset:192
	global_load_dwordx4 v[130:133], v[4:5], off offset:224
	global_load_dwordx4 v[170:173], v[6:7], off
	global_load_dwordx4 v[174:177], v[2:3], off
	v_readlane_b32 s3, v254, 12
	s_add_u32 s2, s46, s2
	s_addc_u32 s3, s47, s3
	s_nop 2
	global_load_dwordx4 v[114:117], v12, s[2:3]
	global_load_dwordx4 v[118:121], v12, s[2:3] offset:32
	global_load_dwordx4 v[122:125], v12, s[2:3] offset:64
	global_load_dwordx4 v[126:129], v12, s[2:3] offset:96
	global_load_dwordx4 v[98:101], v12, s[2:3] offset:128
	global_load_dwordx4 v[102:105], v12, s[2:3] offset:160
	global_load_dwordx4 v[106:109], v12, s[2:3] offset:192
	global_load_dwordx4 v[110:113], v12, s[2:3] offset:224
	v_lshlrev_b32_e32 v3, 8, v1
	v_and_b32_e32 v4, 0xfffff0, v1
	v_lshlrev_b32_e32 v5, 1, v1
	v_lshrrev_b32_e32 v6, 1, v1
	v_bfe_u32 v7, v8, 5, 2
	v_and_b32_e32 v8, 3, v1
	v_add_u32_e32 v1, 32, v1
	v_and_or_b32 v4, v5, 8, v4
	v_and_or_b32 v5, v6, 4, v8
	v_and_b32_e32 v6, 0xfffff0, v1
	v_lshlrev_b32_e32 v8, 1, v1
	v_lshlrev_b32_e32 v12, 1, v9
	s_movk_i32 s2, 0x70
	v_and_or_b32 v6, v8, 8, v6
	v_and_b32_e32 v10, 0x70, v194
	v_bitop3_b32 v13, v12, v194, s2 bitop3:0x78
	v_lshrrev_b32_e32 v4, 1, v4
	v_lshrrev_b32_e32 v6, 1, v6
	v_bitop3_b32 v8, v12, v3, v10 bitop3:0xde
	v_add3_u32 v3, 0, v3, v13
	v_or_b32_e32 v4, v4, v7
	v_or_b32_e32 v6, v6, v7
	v_lshlrev_b32_e32 v5, 6, v5
	v_and_b32_e32 v14, 48, v12
	v_lshlrev_b32_e32 v4, 9, v4
	v_lshlrev_b32_e32 v6, 9, v6
	s_waitcnt vmcnt(0)
	v_lshlrev_b32_e32 v2, 3, v196
	v_or3_b32 v4, v4, v5, v14
	v_or3_b32 v5, v6, v5, v14
	v_lshlrev_b32_e32 v6, 1, v196
	v_and_b32_e32 v6, 32, v6
	s_cmp_lg_u32 0, -1
	v_lshrrev_b32_e32 v11, 5, v196
	s_cselect_b32 s2, 0, 0
	s_waitcnt vmcnt(0)
	ds_write_b128 v3, v[162:165] offset:32768
	ds_write_b128 v3, v[166:169] offset:40960
	v_lshlrev_b32_e32 v3, 4, v196
	v_and_b32_e32 v3, 0xc0, v3
	v_and_or_b32 v3, v2, 24, v3
	v_and_b32_e32 v2, 0x100, v2
	v_or3_b32 v2, v3, v6, v2
	v_lshlrev_b32_e32 v3, 4, v194
	v_add_u32_e32 v220, s2, v2
	v_lshlrev_b32_e32 v2, 4, v11
	v_and_b32_e32 v3, 0x70, v3
	v_xad_u32 v7, v2, v3, 0
	v_or_b32_e32 v10, 32, v2
	v_or_b32_e32 v12, 64, v2
	v_or_b32_e32 v2, 0x60, v2
	v_lshlrev_b32_e32 v200, 2, v11
	s_mov_b32 s10, s58
	v_lshlrev_b32_e32 v6, 8, v195
	v_xad_u32 v10, v10, v3, 0
	v_xad_u32 v12, v12, v3, 0
	v_xad_u32 v13, v2, v3, 0
	v_lshl_or_b32 v2, v1, 7, v9
	v_mov_b32_e32 v3, v0
	v_and_b32_e32 v1, 1, v194
	v_readlane_b32 s2, v253, 21
	s_mov_b32 s75, s33
	v_sub_u32_e32 v197, v195, v200
	s_mov_b32 s58, 0
	v_cmp_gt_u32_e64 s[6:7], 32, v196
	v_lshlrev_b32_e32 v221, 3, v11
	v_cmp_eq_u32_e64 s[8:9], 0, v1
	v_lshl_or_b32 v202, v11, 13, v195
	v_lshlrev_b32_e32 v204, 2, v200
	v_add_u32_e32 v223, 0, v4
	v_add_u32_e32 v224, 0, v5
	v_lshlrev_b64 v[206:207], 1, v[2:3]
	v_add_u32_e32 v225, v7, v6
	v_add_u32_e32 v226, v10, v6
	v_add_u32_e32 v227, v12, v6
	v_add_u32_e32 v228, v13, v6
	v_add_u32_e32 v229, 0, v8
	s_mov_b32 s59, s2
	v_readlane_b32 s14, v253, 16
	v_readlane_b32 s29, v253, 20
	v_readlane_b32 s60, v253, 7
	s_mov_b32 s61, s10
	s_waitcnt lgkmcnt(0)
	s_barrier
	v_readlane_b32 s3, v253, 22
	v_readlane_b32 s15, v253, 17
	s_branch .LBB0_651

; #define KIN(i) ((const float*)KPTR(8 * (i)))
; __global__ void __launch_bounds__(512) fwd_kernel(Params p) {
;     ...
;         case 19: fox::fox_phase((char*)lds_raw, (const fox::bf16*)(R + R_QH), (const fox::bf16*)(R + R_KH), (const fox::bf16*)(R + R_VH), (const float*)(ws + WS_FC), (fox::bf16*)(R + R_O), tid); break;
;         case 25: final_rows(X, KIN(22), (const float*)(ws + WS_SSQ) + (size_t)6 * M, M, gw, ngw, lane); break;
;         default: break;
;         }
;         if (flags & 2) { if (s == 0) grid.sync(); else { const __attribute__((address_space(4))) unsigned char* kb = (const __attribute__((address_space(4))) unsigned char*)__builtin_amdgcn_kernarg_segment_ptr(); asm volatile("" : "+s"(kb));
.LBB0_1306:
	s_setprio 0
	s_bitcmp0_b32 s33, 1
	s_cbranch_scc0 .LBB0_1307
	s_getpc_b64 s[98:99]
